# v35 + FFN-in main loop with half the workgroup barriers: the pre-MFMA barrier only for waves 4-7 and the post-MFMA barrier only for waves 0-3 (offset/align barriers removed)
# baseline (speedup 1.0000x reference)
; #define PG8_STAGE(bufoff, gbase, voff) do { _Pragma("unroll") for (int _i = 0; _i < 2; ++_i) \
;         __builtin_amdgcn_global_load_lds((const unsigned*)((const char*)(gbase) + (voff)[_i]), (LAS unsigned*)(lds + (bufoff) + ldsw + _i * 8192), 16, 0, 0); } while (0)
; #define PG8_WAIT_V(n) asm volatile("s_waitcnt vmcnt(" #n ")" ::: "memory")
; #define PG8_BAR __builtin_amdgcn_s_barrier()
; template <class Epi, class Sched>
; __device__ __forceinline__ void gemm_phase(LAS unsigned char* lds, const Gemm g, const Sched& S, const Epi& E) {
;     ...
;     const int tid = tid_, wid = __builtin_amdgcn_readfirstlane(tid >> 6), lane = tid & 63, wr = wid >> 2, wc = wid & 3, fr = lane & 15, fq = lane >> 4;
;     int K_ = g.K; asm volatile("" : "+s"(K_));
;     const int K = K_, nt = K / BK;
;     unsigned voffA[2], voffB[2];
; #pragma unroll
;     for (int i = 0; i < 2; ++i) { int R, C; stage_rc(tid * 16 + i * 8192, R, C); const int Rb = Epi::PERM ? ((R & ~31) + perm32(R & 31)) : R;
;         voffA[i] = (unsigned)(R * g.lda + C) * 2u; voffB[i] = (unsigned)(Rb * g.ldb + C) * 2u; }
;     const size_t kstep = (size_t)(BK * 2);
;     const size_t hsA = g.hstepA, hsB = g.hstepB;
;     const unsigned ldsw = (unsigned)wid * 1024u;
;     const int aoff = lds_byte(wr * 64 + fr, fq * 8), boff = lds_byte(wc * 32 + fr, fq * 8);
;     ...
;     Unit cur, nxt; int ui = 0;
;     if (!S.next(0, cur)) return;
;     if constexpr (Epi::RSPF) PG8_RSPF(cur);
;     f32x4 acc[2][2][4][2];
; #pragma unroll
;     for (int a = 0; a < 2; ++a)
; #pragma unroll
;         for (int b = 0; b < 2; ++b)
; #pragma unroll
;             for (int m = 0; m < 4; ++m)
; #pragma unroll
;                 for (int n = 0; n < 2; ++n) acc[a][b][m][n] = (f32x4){0.f, 0.f, 0.f, 0.f};
;     bf16x8 At[4][2], B0[2][2], B1[2][2];
;     const char* cA = (const char*)g.A + cur.offA; const char* cB = (const char*)g.Bt + cur.offB;
;     PG8_STAGE(PG8_SB(0, 0), cB, voffB); PG8_STAGE(PG8_SB(0, 1), cB + hsB, voffB); PG8_STAGE(PG8_SA(0, 0), cA, voffA); PG8_STAGE(PG8_SA(0, 1), cA + hsA, voffA);
;     if (wr == 1) PG8_BAR;
;     PG8_WAIT_V(2); PG8_BAR;
;     PG8_STAGE(PG8_SB(1, 0), cB + kstep, voffB); PG8_STAGE(PG8_SA(1, 0), cA + kstep, voffA); PG8_STAGE(PG8_SB(1, 1), cB + hsB + kstep, voffB);
;     PG8_WAIT_V(6); PG8_BAR;
.LBB0_212:
	v_readlane_b32 s8, v252, 43
	s_cmp_eq_u32 s96, 2
	v_mov_b32_e32 v2, v193
	v_readlane_b32 s9, v252, 44
	s_cselect_b64 s[40:41], -1, 0
	s_movk_i32 s1, 0x400
	v_readfirstlane_b32 s0, v2
	s_andn2_b64 vcc, exec, s[8:9]
	s_cbranch_vccnz .LBB0_232
	v_lshlrev_b32_e32 v0, 4, v2
	v_add_u32_e32 v3, 0x2000, v0
	v_ashrrev_i32_e32 v4, 31, v3
	v_lshrrev_b32_e32 v4, 22, v4
	v_add_u32_e32 v4, v3, v4
	v_ashrrev_i32_e32 v10, 10, v4
	v_mul_i32_i24_e32 v4, 0x400, v10
	v_sub_u32_e32 v3, v3, v4
	v_lshrrev_b32_e32 v4, 4, v3
	v_bitop3_b32 v3, v4, v3, 32 bitop3:0x6c
	v_ashrrev_i32_e32 v4, 31, v3
	v_lshrrev_b32_e32 v4, 26, v4
	v_add_u32_e32 v4, v3, v4
	v_lshlrev_b32_e32 v5, 3, v10
	v_ashrrev_i32_e32 v11, 6, v4
	v_and_b32_e32 v5, -16, v5
	v_add_u32_e32 v5, v11, v5
	v_and_b32_e32 v6, 3, v11
	s_mov_b32 s10, 0x1fffe0
	v_lshrrev_b32_e32 v7, 2, v5
	v_lshlrev_b32_e32 v8, 1, v5
	v_and_b32_e32 v4, 0xc0, v4
	v_and_or_b32 v6, v5, s10, v6
	v_and_b32_e32 v7, 4, v7
	v_and_b32_e32 v8, 24, v8
	v_sub_u32_e32 v3, v3, v4
	v_or3_b32 v6, v6, v7, v8
	v_lshlrev_b32_e32 v7, 5, v10
	v_ashrrev_i16_sdwa v3, v234, sext(v3) dst_sel:DWORD dst_unused:UNUSED_PAD src0_sel:DWORD src1_sel:BYTE_0
	v_and_b32_e32 v7, 32, v7
	v_bfe_i32 v12, v3, 0, 16
	v_add_lshl_u32 v3, v7, v12, 1
	v_lshl_add_u32 v130, v6, 11, v3
	v_lshl_add_u32 v132, v5, 11, v3
	v_bfe_i32 v3, v2, 27, 1
	v_lshrrev_b32_e32 v3, 22, v3
	v_add_u32_e32 v3, v0, v3
	v_and_b32_e32 v3, 0xfffffc00, v3
	v_sub_u32_e32 v0, v0, v3
	v_lshrrev_b32_e32 v3, 4, v0
	v_bitop3_b32 v0, v3, v0, 32 bitop3:0x6c
	v_ashrrev_i32_e32 v3, 31, v0
	v_lshrrev_b32_e32 v3, 26, v3
	v_add_u32_e32 v4, v0, v3
	v_ashrrev_i32_e32 v3, 31, v2
	v_lshrrev_b32_e32 v5, 26, v3
	v_add_u32_e32 v5, v2, v5
	v_ashrrev_i32_e32 v14, 6, v5
	v_lshlrev_b32_e32 v5, 3, v14
	v_ashrrev_i32_e32 v13, 6, v4
	v_and_b32_e32 v5, -16, v5
	v_writelane_b32 v250, s40, 44
	s_and_b64 s[8:9], s[40:41], exec
	v_add_u32_e32 v5, v13, v5
	s_cselect_b32 s7, 0x1c00000, 0
	v_readlane_b32 s8, v251, 27
	v_and_b32_e32 v6, 3, v13
	v_lshrrev_b32_e32 v7, 2, v5
	v_lshlrev_b32_e32 v8, 1, v5
	v_and_b32_e32 v4, 0xc0, v4
	s_add_u32 s7, s8, s7
	v_readlane_b32 s8, v251, 28
	v_and_or_b32 v6, v5, s10, v6
	v_and_b32_e32 v7, 4, v7
	v_and_b32_e32 v8, 24, v8
	v_sub_u32_e32 v0, v0, v4
	s_addc_u32 s11, s8, 0
	s_ashr_i32 s8, s0, 6
	v_or3_b32 v6, v6, v7, v8
	v_lshlrev_b32_e32 v7, 5, v14
	v_ashrrev_i16_sdwa v0, v234, sext(v0) dst_sel:DWORD dst_unused:UNUSED_PAD src0_sel:DWORD src1_sel:BYTE_0
	v_writelane_b32 v250, s41, 45
	s_lshl_b32 s12, s8, 10
	v_and_b32_e32 v7, 32, v7
	v_bfe_i32 v15, v0, 0, 16
	v_add_lshl_u32 v4, v7, v15, 1
	v_readlane_b32 s20, v250, 9
	s_add_i32 s16, s12, 0
	v_lshl_add_u32 v0, v6, 11, v4
	v_lshl_add_u32 v134, v5, 11, v4
	v_lshlrev_b64 v[4:5], 4, v[2:3]
	v_readlane_b32 s21, v250, 10
	s_add_i32 s24, s16, 0x21000
	s_mov_b32 m0, s24
	v_lshl_add_u64 v[6:7], s[20:21], 0, v[4:5]
	s_mov_b64 s[20:21], 0x2000
	s_ashr_i32 s9, s0, 8
	global_load_lds_dwordx4 v[6:7], off
	v_lshl_add_u64 v[6:7], v[6:7], 0, s[20:21]
	s_add_i32 s26, s16, 0x23000
	v_readlane_b32 s20, v253, 5
	s_mov_b32 m0, s26
	v_readlane_b32 s21, v253, 6
	s_add_u32 s38, s7, s20
	global_load_lds_dwordx4 v[6:7], off
	s_addc_u32 s39, s11, s21
	s_add_i32 m0, s16, 0x10000
	v_mov_b32_e32 v131, v1
	global_load_lds_dwordx4 v0, s[38:39]
	s_add_i32 m0, s16, 0x12000
	s_add_u32 s20, s38, 0x40000
	global_load_lds_dwordx4 v130, s[38:39]
	s_addc_u32 s21, s39, 0
	s_add_i32 m0, s16, 0x14000
	s_add_i32 s30, s16, 0x2000
	global_load_lds_dwordx4 v0, s[20:21]
	s_add_i32 m0, s16, 0x16000
	s_add_i32 s52, s16, 0x4000
	global_load_lds_dwordx4 v130, s[20:21]
	v_readlane_b32 s20, v250, 11
	s_mov_b32 m0, s16
	v_readlane_b32 s21, v250, 12
	s_add_i32 s56, s16, 0x6000
	s_cmp_eq_u32 s9, 1
	v_lshl_add_u64 v[6:7], s[38:39], 0, v[0:1]
	s_cselect_b64 s[36:37], -1, 0
	s_cmp_lg_u32 s9, 1
	global_load_lds_dwordx4 v134, s[20:21]
	s_mov_b32 m0, s30
	v_lshl_add_u64 v[8:9], s[38:39], 0, v[130:131]
	global_load_lds_dwordx4 v132, s[20:21]
	v_readlane_b32 s20, v250, 13
	s_mov_b32 m0, s52
	v_readlane_b32 s21, v250, 14
	s_nop 4
	global_load_lds_dwordx4 v134, s[20:21]
	s_mov_b32 m0, s56
	s_nop 0
	global_load_lds_dwordx4 v132, s[20:21]
	s_cbranch_scc1 .LBB0_215
.LBB0_215:
	s_ashr_i32 s10, s1, 31
	v_readlane_b32 s22, v250, 11
	s_lshr_b32 s10, s10, 26
	s_lshl_b32 s8, s8, 5
	v_mov_b32_e32 v135, v1
	v_readlane_b32 s23, v250, 12
	s_add_i32 s10, s1, s10
	s_and_b32 s73, s8, 0x60
	s_add_i32 m0, s16, 0x18000
	v_lshl_add_u64 v[6:7], v[6:7], 0, s[18:19]
	v_lshl_add_u64 v[16:17], s[22:23], 0, v[134:135]
	v_mov_b32_e32 v133, v1
	s_ashr_i32 s57, s10, 6
	s_lshl_b32 s64, s9, 6
	s_lshl_b32 s10, s9, 13
	s_lshl_b32 s20, s73, 7
	s_waitcnt vmcnt(2)
	s_barrier
	global_load_lds_dwordx4 v[6:7], off
	v_lshl_add_u64 v[6:7], v[8:9], 0, s[18:19]
	s_add_i32 m0, s16, 0x1a000
	s_add_i32 s78, s16, 0x8000
	s_add_i32 s80, s16, 0xa000
	v_lshl_add_u64 v[18:19], s[22:23], 0, v[132:133]
	global_load_lds_dwordx4 v[6:7], off
	v_lshl_add_u64 v[6:7], v[16:17], 0, s[18:19]
	s_mov_b32 m0, s78
	s_add_u32 s8, s38, 0x40080
	global_load_lds_dwordx4 v[6:7], off
	v_lshl_add_u64 v[6:7], v[18:19], 0, s[18:19]
	s_mov_b32 m0, s80
	s_addc_u32 s9, s39, 0
	global_load_lds_dwordx4 v[6:7], off
	s_add_i32 m0, s16, 0x1c000
	v_lshl_add_u64 v[6:7], s[8:9], 0, v[0:1]
	global_load_lds_dwordx4 v[6:7], off
	v_lshl_add_u64 v[6:7], s[8:9], 0, v[130:131]
	s_add_i32 m0, s16, 0x1e000
	v_bfe_u32 v159, v2, 4, 2
	global_load_lds_dwordx4 v[6:7], off
	v_and_b32_e32 v158, 15, v2
	v_lshlrev_b32_e32 v3, 4, v159
	v_lshlrev_b32_e32 v2, 2, v2
	v_lshl_or_b32 v3, v158, 6, v3
	v_and_b32_e32 v2, 32, v2
	v_bitop3_b32 v6, v3, s10, v2 bitop3:0xde
	v_bitop3_b32 v160, v3, s20, v2 bitop3:0xde
	v_lshlrev_b32_e32 v2, 14, v14
	v_and_b32_e32 v2, 0xffff8000, v2
	v_lshl_add_u32 v2, v13, 11, v2
	v_and_b32_e32 v3, 1, v14
	v_lshl_or_b32 v2, v3, 6, v2
	s_cmp_gt_i32 s1, 63
	v_lshl_add_u32 v138, v15, 1, v2
	v_lshlrev_b32_e32 v2, 14, v10
	s_cselect_b64 s[74:75], -1, 0
	s_add_i32 s82, s57, -2
	v_and_b32_e32 v2, 0xffff8000, v2
	s_waitcnt vmcnt(6)
	v_readlane_b32 s8, v250, 21
	s_cmpk_lt_u32 s0, 0x100
	v_lshl_add_u32 v2, v11, 11, v2
	v_and_b32_e32 v3, 1, v10
	v_readlane_b32 s0, v253, 10
	v_readlane_b32 s9, v250, 22
	v_lshl_or_b32 v2, v3, 6, v2
	v_readlane_b32 s1, v253, 11
	v_lshl_add_u64 v[136:137], s[8:9], 0, v[4:5]
	s_cselect_b64 s[34:35], -1, 0
	v_mov_b32_e32 v139, v1
	v_lshl_add_u32 v140, v12, 1, v2
	v_mov_b32_e32 v141, v1
	s_mov_b32 s83, 0
	v_add_u32_e32 v161, 0, v6
	s_mov_b32 s40, s0
	v_readlane_b32 s41, v253, 4
	s_mov_b64 s[0:1], s[22:23]
	v_writelane_b32 v250, s36, 46
	s_barrier
	s_nop 0
	v_writelane_b32 v250, s37, 47
	s_branch .LBB0_218

; #define PG8_STAGE(bufoff, gbase, voff) do { _Pragma("unroll") for (int _i = 0; _i < 2; ++_i) \
;         __builtin_amdgcn_global_load_lds((const unsigned*)((const char*)(gbase) + (voff)[_i]), (LAS unsigned*)(lds + (bufoff) + ldsw + _i * 8192), 16, 0, 0); } while (0)
; #define PG8_LDA(dst, b, h) do { _Pragma("unroll") for (int m = 0; m < 4; ++m) _Pragma("unroll") for (int k = 0; k < 2; ++k) dst[m][k] = *(const LAS bf16x8*)(lds + PG8_SA(b, h) + aoff + m * 2048 + k * 1024); } while (0)
; #define PG8_LDB(dst, b, h) do { _Pragma("unroll") for (int n = 0; n < 2; ++n) _Pragma("unroll") for (int k = 0; k < 2; ++k) dst[n][k] = *(const LAS bf16x8*)(lds + PG8_SB(b, h) + boff + n * 2048 + k * 1024); } while (0)
; #define PG8_MMA(ai, bj, At, Bt) do { __builtin_amdgcn_s_setprio(1); _Pragma("unroll") for (int m = 0; m < 4; ++m) _Pragma("unroll") for (int n = 0; n < 2; ++n) _Pragma("unroll") for (int k = 0; k < 2; ++k) \
;         acc[ai][bj][m][n] = __builtin_amdgcn_mfma_f32_16x16x32_bf16(Bt[n][k], At[m][k], acc[ai][bj][m][n], 0, 0, 0); __builtin_amdgcn_s_setprio(0); } while (0)
; #define PG8_WAIT_V(n) asm volatile("s_waitcnt vmcnt(" #n ")" ::: "memory")
; #define PG8_WAIT_L(n) asm volatile("s_waitcnt lgkmcnt(" #n ")" ::: "memory")
; #define PG8_BAR __builtin_amdgcn_s_barrier()
; #define PG8_SCHED __builtin_amdgcn_sched_barrier(0)
; template <class Epi, class Sched>
; __device__ __forceinline__ void gemm_phase(LAS unsigned char* lds, const Gemm g, const Sched& S, const Epi& E) {
;     ...
;             PG8_LDB(B0, 0, 0); PG8_LDB(B1, 0, 1); PG8_SCHED; PG8_LDA(At, 0, 0); PG8_STAGE(PG8_SA(1, 1), a1 + hsA, voffA);
;             PG8_WAIT_V(8); PG8_WAIT_L(0); PG8_BAR; PG8_MMA(0, 0, At, B0); PG8_MMA(0, 1, At, B1); PG8_BAR; PG8_SCHED;
.Lnp_222:
.LBB0_222:
	s_add_i32 s96, s9, 2
	s_add_u32 s20, s0, 0xfffc0080
	s_addc_u32 s21, s1, -1
	s_add_i32 s74, 0, 0x10000
	s_cmp_eq_u32 s82, s9
	s_cselect_b32 s85, s10, s21
	s_cselect_b32 s84, s43, s20
	s_cselect_b32 s39, s45, s8
	s_cselect_b32 s38, vcc_lo, vcc_hi
	s_add_i32 s9, 0, 0x14000
	v_add_u32_e32 v154, s74, v160
	v_add_u32_e32 v174, s9, v160
	ds_read_b128 v[142:145], v154
	ds_read_b128 v[146:149], v154 offset:1024
	ds_read_b128 v[150:153], v154 offset:2048
	ds_read_b128 v[154:157], v154 offset:3072
	ds_read_b128 v[162:165], v174
	ds_read_b128 v[166:169], v174 offset:1024
	ds_read_b128 v[170:173], v174 offset:2048
	ds_read_b128 v[174:177], v174 offset:3072
	v_lshl_add_u64 v[190:191], s[0:1], 0, v[138:139]
	s_add_i32 m0, s16, 0xc000
	ds_read_b128 v[178:181], v161
	ds_read_b128 v[182:185], v161 offset:1024
	ds_read_b128 v[186:189], v161 offset:2048
	ds_read_b128 v[208:211], v161 offset:3072
	ds_read_b128 v[212:215], v161 offset:4096
	ds_read_b128 v[216:219], v161 offset:5120
	ds_read_b128 v[220:223], v161 offset:6144
	ds_read_b128 v[224:227], v161 offset:7168
	global_load_lds_dwordx4 v[190:191], off
	v_lshl_add_u64 v[190:191], s[0:1], 0, v[140:141]
	s_add_i32 m0, s16, 0xe000
	s_nop 0
	global_load_lds_dwordx4 v[190:191], off
	s_waitcnt vmcnt(8)
	s_waitcnt lgkmcnt(0)
	v_readfirstlane_b32 s20, v193
	s_bitcmp1_b32 s20, 8
	s_cbranch_scc0 .Lhb_ffnin_1
	s_barrier
.Lhb_ffnin_1:
	s_waitcnt lgkmcnt(0)
	v_mfma_f32_16x16x32_bf16 v[122:125], v[142:145], v[178:181], v[122:125]
	v_mfma_f32_16x16x32_bf16 v[114:117], v[150:153], v[178:181], v[114:117]
	v_mfma_f32_16x16x32_bf16 v[106:109], v[142:145], v[186:189], v[106:109]
	v_mfma_f32_16x16x32_bf16 v[98:101], v[150:153], v[186:189], v[98:101]
	v_mfma_f32_16x16x32_bf16 v[90:93], v[142:145], v[212:215], v[90:93]
	v_mfma_f32_16x16x32_bf16 v[82:85], v[150:153], v[212:215], v[82:85]
	v_mfma_f32_16x16x32_bf16 v[74:77], v[142:145], v[220:223], v[74:77]
	v_mfma_f32_16x16x32_bf16 v[66:69], v[150:153], v[220:223], v[66:69]
	v_mfma_f32_16x16x32_bf16 v[122:125], v[146:149], v[182:185], v[122:125]
	v_mfma_f32_16x16x32_bf16 v[114:117], v[154:157], v[182:185], v[114:117]
	v_mfma_f32_16x16x32_bf16 v[106:109], v[146:149], v[208:211], v[106:109]
	v_mfma_f32_16x16x32_bf16 v[98:101], v[154:157], v[208:211], v[98:101]
	v_mfma_f32_16x16x32_bf16 v[90:93], v[146:149], v[216:219], v[90:93]
	v_mfma_f32_16x16x32_bf16 v[82:85], v[154:157], v[216:219], v[82:85]
	v_mfma_f32_16x16x32_bf16 v[74:77], v[146:149], v[224:227], v[74:77]
	v_mfma_f32_16x16x32_bf16 v[66:69], v[154:157], v[224:227], v[66:69]
	v_mfma_f32_16x16x32_bf16 v[126:129], v[162:165], v[178:181], v[126:129]
	v_mfma_f32_16x16x32_bf16 v[118:121], v[170:173], v[178:181], v[118:121]
	v_mfma_f32_16x16x32_bf16 v[110:113], v[162:165], v[186:189], v[110:113]
	v_mfma_f32_16x16x32_bf16 v[102:105], v[170:173], v[186:189], v[102:105]
	v_mfma_f32_16x16x32_bf16 v[94:97], v[162:165], v[212:215], v[94:97]
	v_mfma_f32_16x16x32_bf16 v[86:89], v[170:173], v[212:215], v[86:89]
	v_mfma_f32_16x16x32_bf16 v[78:81], v[162:165], v[220:223], v[78:81]
	v_mfma_f32_16x16x32_bf16 v[70:73], v[170:173], v[220:223], v[70:73]
	v_mfma_f32_16x16x32_bf16 v[126:129], v[166:169], v[182:185], v[126:129]
	v_mfma_f32_16x16x32_bf16 v[118:121], v[174:177], v[182:185], v[118:121]
	v_mfma_f32_16x16x32_bf16 v[110:113], v[166:169], v[208:211], v[110:113]
	v_mfma_f32_16x16x32_bf16 v[102:105], v[174:177], v[208:211], v[102:105]
	v_mfma_f32_16x16x32_bf16 v[94:97], v[166:169], v[216:219], v[94:97]
	v_mfma_f32_16x16x32_bf16 v[86:89], v[174:177], v[216:219], v[86:89]
	v_mfma_f32_16x16x32_bf16 v[78:81], v[166:169], v[224:227], v[78:81]
	v_mfma_f32_16x16x32_bf16 v[70:73], v[174:177], v[224:227], v[70:73]
	v_readfirstlane_b32 s20, v193
	s_bitcmp1_b32 s20, 8
	s_cbranch_scc1 .Lhb_ffnin_2
	s_barrier
; #define PG8_STAGE(bufoff, gbase, voff) do { _Pragma("unroll") for (int _i = 0; _i < 2; ++_i) \
;         __builtin_amdgcn_global_load_lds((const unsigned*)((const char*)(gbase) + (voff)[_i]), (LAS unsigned*)(lds + (bufoff) + ldsw + _i * 8192), 16, 0, 0); } while (0)
; #define PG8_LDA(dst, b, h) do { _Pragma("unroll") for (int m = 0; m < 4; ++m) _Pragma("unroll") for (int k = 0; k < 2; ++k) dst[m][k] = *(const LAS bf16x8*)(lds + PG8_SA(b, h) + aoff + m * 2048 + k * 1024); } while (0)
; #define PG8_LDB(dst, b, h) do { _Pragma("unroll") for (int n = 0; n < 2; ++n) _Pragma("unroll") for (int k = 0; k < 2; ++k) dst[n][k] = *(const LAS bf16x8*)(lds + PG8_SB(b, h) + boff + n * 2048 + k * 1024); } while (0)
; #define PG8_MMA(ai, bj, At, Bt) do { __builtin_amdgcn_s_setprio(1); _Pragma("unroll") for (int m = 0; m < 4; ++m) _Pragma("unroll") for (int n = 0; n < 2; ++n) _Pragma("unroll") for (int k = 0; k < 2; ++k) \
;         acc[ai][bj][m][n] = __builtin_amdgcn_mfma_f32_16x16x32_bf16(Bt[n][k], At[m][k], acc[ai][bj][m][n], 0, 0, 0); __builtin_amdgcn_s_setprio(0); } while (0)
; #define PG8_WAIT_V(n) asm volatile("s_waitcnt vmcnt(" #n ")" ::: "memory")
; #define PG8_WAIT_L(n) asm volatile("s_waitcnt lgkmcnt(" #n ")" ::: "memory")
; #define PG8_BAR __builtin_amdgcn_s_barrier()
; #define PG8_SCHED __builtin_amdgcn_sched_barrier(0)
; template <class Epi, class Sched>
; __device__ __forceinline__ void gemm_phase(LAS unsigned char* lds, const Gemm g, const Sched& S, const Epi& E) {
;     ...
;             PG8_LDA(At, 0, 1); PG8_STAGE(PG8_SB(0, 0), b2, voffB); PG8_STAGE(PG8_SB(0, 1), b2 + hsB, voffB); PG8_STAGE(PG8_SA(0, 0), a2, voffA);
;             PG8_WAIT_V(8); PG8_WAIT_L(0); PG8_BAR; PG8_MMA(1, 0, At, B0); PG8_MMA(1, 1, At, B1); PG8_BAR; PG8_SCHED;
;             PG8_LDB(B0, 1, 0); PG8_LDB(B1, 1, 1); PG8_SCHED; PG8_LDA(At, 1, 0); PG8_STAGE(PG8_SA(0, 1), a2 + hsA, voffA);
;             PG8_WAIT_V(8); PG8_WAIT_L(0); PG8_BAR; PG8_MMA(0, 0, At, B0); PG8_MMA(0, 1, At, B1); PG8_BAR; PG8_SCHED;
.Lhb_ffnin_2:
	s_add_i32 s20, s74, s12
	v_lshl_add_u64 v[190:191], s[38:39], 0, v[0:1]
	s_mov_b32 m0, s20
	ds_read_b128 v[178:181], v161 offset:16384
	ds_read_b128 v[182:185], v161 offset:17408
	ds_read_b128 v[186:189], v161 offset:18432
	ds_read_b128 v[208:211], v161 offset:19456
	ds_read_b128 v[212:215], v161 offset:20480
	ds_read_b128 v[216:219], v161 offset:21504
	ds_read_b128 v[220:223], v161 offset:22528
	ds_read_b128 v[224:227], v161 offset:23552
	global_load_lds_dwordx4 v[190:191], off
	s_add_i32 m0, s20, 0x2000
	s_add_u32 s20, s38, 0x40000
	v_lshl_add_u64 v[228:229], s[38:39], 0, v[130:131]
	s_addc_u32 s21, s39, 0
	s_add_i32 s9, s9, s12
	global_load_lds_dwordx4 v[228:229], off
	v_lshl_add_u64 v[230:231], s[20:21], 0, v[0:1]
	s_mov_b32 m0, s9
	v_lshl_add_u64 v[232:233], s[84:85], 0, v[132:133]
	global_load_lds_dwordx4 v[230:231], off
	v_lshl_add_u64 v[230:231], s[20:21], 0, v[130:131]
	s_add_i32 m0, s9, 0x2000
	s_nop 0
	global_load_lds_dwordx4 v[230:231], off
	v_lshl_add_u64 v[230:231], s[84:85], 0, v[134:135]
	s_mov_b32 m0, s16
	s_nop 0
	global_load_lds_dwordx4 v[230:231], off
	s_mov_b32 m0, s30
	s_nop 0
	global_load_lds_dwordx4 v[232:233], off
	s_waitcnt vmcnt(8)
	s_waitcnt lgkmcnt(0)
	v_readfirstlane_b32 s20, v193
	s_bitcmp1_b32 s20, 8
	s_cbranch_scc0 .Lhb_ffnin_3
	s_barrier
.Lhb_ffnin_3:
	s_waitcnt lgkmcnt(0)
	v_mfma_f32_16x16x32_bf16 v[58:61], v[142:145], v[178:181], v[58:61]
	v_mfma_f32_16x16x32_bf16 v[50:53], v[150:153], v[178:181], v[50:53]
	v_mfma_f32_16x16x32_bf16 v[42:45], v[142:145], v[186:189], v[42:45]
	v_mfma_f32_16x16x32_bf16 v[34:37], v[150:153], v[186:189], v[34:37]
	v_mfma_f32_16x16x32_bf16 v[26:29], v[142:145], v[212:215], v[26:29]
	v_mfma_f32_16x16x32_bf16 v[18:21], v[150:153], v[212:215], v[18:21]
	v_mfma_f32_16x16x32_bf16 v[10:13], v[142:145], v[220:223], v[10:13]
	v_mfma_f32_16x16x32_bf16 v[2:5], v[150:153], v[220:223], v[2:5]
	v_mfma_f32_16x16x32_bf16 v[58:61], v[146:149], v[182:185], v[58:61]
	v_mfma_f32_16x16x32_bf16 v[50:53], v[154:157], v[182:185], v[50:53]
	v_mfma_f32_16x16x32_bf16 v[42:45], v[146:149], v[208:211], v[42:45]
	v_mfma_f32_16x16x32_bf16 v[34:37], v[154:157], v[208:211], v[34:37]
	v_mfma_f32_16x16x32_bf16 v[26:29], v[146:149], v[216:219], v[26:29]
	v_mfma_f32_16x16x32_bf16 v[18:21], v[154:157], v[216:219], v[18:21]
	v_mfma_f32_16x16x32_bf16 v[10:13], v[146:149], v[224:227], v[10:13]
	v_mfma_f32_16x16x32_bf16 v[2:5], v[154:157], v[224:227], v[2:5]
	v_mfma_f32_16x16x32_bf16 v[62:65], v[162:165], v[178:181], v[62:65]
	v_mfma_f32_16x16x32_bf16 v[54:57], v[170:173], v[178:181], v[54:57]
	v_mfma_f32_16x16x32_bf16 v[46:49], v[162:165], v[186:189], v[46:49]
	v_mfma_f32_16x16x32_bf16 v[38:41], v[170:173], v[186:189], v[38:41]
	v_mfma_f32_16x16x32_bf16 v[30:33], v[162:165], v[212:215], v[30:33]
	v_mfma_f32_16x16x32_bf16 v[22:25], v[170:173], v[212:215], v[22:25]
	v_mfma_f32_16x16x32_bf16 v[14:17], v[162:165], v[220:223], v[14:17]
	v_mfma_f32_16x16x32_bf16 v[6:9], v[170:173], v[220:223], v[6:9]
	v_mfma_f32_16x16x32_bf16 v[62:65], v[166:169], v[182:185], v[62:65]
	v_mfma_f32_16x16x32_bf16 v[54:57], v[174:177], v[182:185], v[54:57]
	v_mfma_f32_16x16x32_bf16 v[46:49], v[166:169], v[208:211], v[46:49]
	v_mfma_f32_16x16x32_bf16 v[38:41], v[174:177], v[208:211], v[38:41]
	v_mfma_f32_16x16x32_bf16 v[30:33], v[166:169], v[216:219], v[30:33]
	v_mfma_f32_16x16x32_bf16 v[22:25], v[174:177], v[216:219], v[22:25]
	v_mfma_f32_16x16x32_bf16 v[14:17], v[166:169], v[224:227], v[14:17]
	v_mfma_f32_16x16x32_bf16 v[6:9], v[174:177], v[224:227], v[6:9]
	v_readfirstlane_b32 s20, v193
	s_bitcmp1_b32 s20, 8
	s_cbranch_scc1 .Lhb_ffnin_4
	s_barrier
.Lhb_ffnin_4:
	s_add_i32 s9, 0, 0x18000
	s_add_i32 s74, 0, 0x1c000
	v_add_u32_e32 v154, s9, v160
	v_add_u32_e32 v174, s74, v160
	ds_read_b128 v[142:145], v154
	ds_read_b128 v[146:149], v154 offset:1024
	ds_read_b128 v[150:153], v154 offset:2048
	ds_read_b128 v[154:157], v154 offset:3072
	ds_read_b128 v[162:165], v174
	ds_read_b128 v[166:169], v174 offset:1024
	ds_read_b128 v[170:173], v174 offset:2048
	ds_read_b128 v[174:177], v174 offset:3072
	s_add_u32 s20, s84, 0x40000
	s_addc_u32 s21, s85, 0
	s_mov_b32 m0, s52
	v_lshl_add_u64 v[238:239], s[20:21], 0, v[134:135]
	ds_read_b128 v[178:181], v161 offset:32768
	ds_read_b128 v[182:185], v161 offset:33792
	ds_read_b128 v[186:189], v161 offset:34816
	ds_read_b128 v[208:211], v161 offset:35840
	ds_read_b128 v[212:215], v161 offset:36864
	ds_read_b128 v[216:219], v161 offset:37888
	ds_read_b128 v[220:223], v161 offset:38912
	ds_read_b128 v[224:227], v161 offset:39936
	global_load_lds_dwordx4 v[238:239], off
	v_lshl_add_u64 v[238:239], s[20:21], 0, v[132:133]
	s_mov_b32 m0, s56
	s_nop 0
	global_load_lds_dwordx4 v[238:239], off
	s_waitcnt vmcnt(8)
	s_waitcnt lgkmcnt(0)
	v_readfirstlane_b32 s20, v193
	s_bitcmp1_b32 s20, 8
	s_cbranch_scc0 .Lhb_ffnin_5
	s_barrier

; #define PG8_STAGE(bufoff, gbase, voff) do { _Pragma("unroll") for (int _i = 0; _i < 2; ++_i) \
;         __builtin_amdgcn_global_load_lds((const unsigned*)((const char*)(gbase) + (voff)[_i]), (LAS unsigned*)(lds + (bufoff) + ldsw + _i * 8192), 16, 0, 0); } while (0)
; #define PG8_LDA(dst, b, h) do { _Pragma("unroll") for (int m = 0; m < 4; ++m) _Pragma("unroll") for (int k = 0; k < 2; ++k) dst[m][k] = *(const LAS bf16x8*)(lds + PG8_SA(b, h) + aoff + m * 2048 + k * 1024); } while (0)
; #define PG8_MMA(ai, bj, At, Bt) do { __builtin_amdgcn_s_setprio(1); _Pragma("unroll") for (int m = 0; m < 4; ++m) _Pragma("unroll") for (int n = 0; n < 2; ++n) _Pragma("unroll") for (int k = 0; k < 2; ++k) \
;         acc[ai][bj][m][n] = __builtin_amdgcn_mfma_f32_16x16x32_bf16(Bt[n][k], At[m][k], acc[ai][bj][m][n], 0, 0, 0); __builtin_amdgcn_s_setprio(0); } while (0)
; #define PG8_WAIT_V(n) asm volatile("s_waitcnt vmcnt(" #n ")" ::: "memory")
; #define PG8_WAIT_L(n) asm volatile("s_waitcnt lgkmcnt(" #n ")" ::: "memory")
; #define PG8_BAR __builtin_amdgcn_s_barrier()
; #define PG8_SCHED __builtin_amdgcn_sched_barrier(0)
; template <class Epi, class Sched>
; __device__ __forceinline__ void gemm_phase(LAS unsigned char* lds, const Gemm g, const Sched& S, const Epi& E) {
;     ...
;             PG8_LDA(At, 1, 1); PG8_STAGE(PG8_SB(1, 0), b3, voffB); PG8_STAGE(PG8_SB(1, 1), b3 + hsB, voffB); PG8_STAGE(PG8_SA(1, 0), a3, voffA);
;             PG8_WAIT_V(8); PG8_WAIT_L(0); PG8_BAR; PG8_MMA(1, 0, At, B0); PG8_MMA(1, 1, At, B1); PG8_BAR; PG8_SCHED;
.Lhb_ffnin_6:
	s_add_i32 s9, s9, s12
	v_lshl_add_u64 v[190:191], v[190:191], 0, s[18:19]
	s_mov_b32 m0, s9
	ds_read_b128 v[178:181], v161 offset:49152
	ds_read_b128 v[182:185], v161 offset:50176
	ds_read_b128 v[186:189], v161 offset:51200
	ds_read_b128 v[208:211], v161 offset:52224
	ds_read_b128 v[212:215], v161 offset:53248
	ds_read_b128 v[216:219], v161 offset:54272
	ds_read_b128 v[220:223], v161 offset:55296
	ds_read_b128 v[224:227], v161 offset:56320
	global_load_lds_dwordx4 v[190:191], off
	s_add_i32 m0, s9, 0x2000
	s_add_u32 s20, s38, 0x40080
	v_lshl_add_u64 v[190:191], v[228:229], 0, s[18:19]
	s_addc_u32 s21, s39, 0
	s_add_i32 s9, s74, s12
	global_load_lds_dwordx4 v[190:191], off
	v_lshl_add_u64 v[190:191], s[20:21], 0, v[0:1]
	s_mov_b32 m0, s9
	s_nop 0
	global_load_lds_dwordx4 v[190:191], off
	v_lshl_add_u64 v[190:191], s[20:21], 0, v[130:131]
	s_add_i32 m0, s9, 0x2000
	s_nop 0
	global_load_lds_dwordx4 v[190:191], off
	v_lshl_add_u64 v[190:191], v[230:231], 0, s[18:19]
	s_mov_b32 m0, s78
	s_nop 0
	global_load_lds_dwordx4 v[190:191], off
	v_lshl_add_u64 v[190:191], v[232:233], 0, s[18:19]
	s_mov_b32 m0, s80
	s_nop 0
	global_load_lds_dwordx4 v[190:191], off
	s_waitcnt vmcnt(8)
	s_waitcnt lgkmcnt(0)
	v_readfirstlane_b32 s20, v193
	s_bitcmp1_b32 s20, 8
	s_cbranch_scc0 .Lhb_ffnin_7
	s_barrier

; #define LAS __attribute__((address_space(3)))
; #define PG8_MMA(ai, bj, At, Bt) do { __builtin_amdgcn_s_setprio(1); _Pragma("unroll") for (int m = 0; m < 4; ++m) _Pragma("unroll") for (int n = 0; n < 2; ++n) _Pragma("unroll") for (int k = 0; k < 2; ++k) \
;         acc[ai][bj][m][n] = __builtin_amdgcn_mfma_f32_16x16x32_bf16(Bt[n][k], At[m][k], acc[ai][bj][m][n], 0, 0, 0); __builtin_amdgcn_s_setprio(0); } while (0)
; #define PG8_WAIT_V(n) asm volatile("s_waitcnt vmcnt(" #n ")" ::: "memory")
; #define PG8_WAIT_L(n) asm volatile("s_waitcnt lgkmcnt(" #n ")" ::: "memory")
; #define PG8_BAR __builtin_amdgcn_s_barrier()
; #define PG8_SCHED __builtin_amdgcn_sched_barrier(0)
; #define PG8_RSPF(un) do { const char* _s = (const char*)E.ssq + (size_t)(un).pm * (256 * 64) + (size_t)tid * 16; \
;         __builtin_amdgcn_global_load_lds((const unsigned*)_s, (LAS unsigned*)(lds + LDS_RS + ldsw), 16, 0, 0); \
;         __builtin_amdgcn_global_load_lds((const unsigned*)(_s + 8192), (LAS unsigned*)(lds + LDS_RS + 8192 + ldsw), 16, 0, 0); } while (0)
; __device__ __forceinline__ void rows_rs8_lds(const LAS unsigned char* lds, int rt0, int fq, float (&rs)[2][4]) {
;     const LAS f32x4* rp = (const LAS f32x4*)(lds + LDS_RS);
; #pragma unroll
;     for (int ai = 0; ai < 2; ++ai)
; #pragma unroll
;         for (int m = 0; m < 4; ++m) { const f32x4 p = rp[(rt0 + ai * 128 + m * 16) * 4 + fq]; float s = (p[0] + p[1]) + (p[2] + p[3]); s += __shfl_xor(s, 16); s += __shfl_xor(s, 32); rs[ai][m] = rsqrtf(s * (1.0f / 1024.0f) + EPS); }
; }
; template <class Epi, class Sched>
; __device__ __forceinline__ void gemm_phase(LAS unsigned char* lds, const Gemm g, const Sched& S, const Epi& E) {
;     ...
;             PG8_WAIT_V(8); PG8_WAIT_L(0); PG8_BAR; PG8_MMA(1, 0, At, B0); PG8_MMA(1, 1, At, B1); PG8_BAR; PG8_SCHED;
;         }
;         if (wr == 0) PG8_BAR;
;         { int fr_ = fr, fq_ = fq; asm volatile("" : "+v"(fr_), "+v"(fq_));
;           if constexpr (Epi::RSPF) {
;               float rsv[2][4]; rows_rs8_lds(lds, wr * 64 + fr_, fq_, rsv);
;               PG8_WAIT_L(0); PG8_BAR;
;               if (has_next) PG8_RSPF(nxt);
.Lhb_ffnin_8:
	s_add_u32 s0, s0, 0x100
	s_addc_u32 s1, s1, 0
	s_add_u32 vcc_hi, vcc_hi, 0x100
	s_addc_u32 s8, s8, 0
	s_cmp_ge_i32 s96, s57
	s_mov_b32 s9, s96
	s_cbranch_scc0 .LBB0_222
	s_setprio 0
	v_readlane_b32 s96, v250, 43
	s_mov_b64 s[74:75], s[22:23]
.LBB0_224:
	s_and_b64 vcc, exec, s[34:35]
	s_cbranch_vccz .LBB0_226
.LBB0_226:
	v_mov_b32_e32 v142, v158
	v_mov_b32_e32 v162, v159
	s_add_i32 s0, 0, 0x21000
	v_add_u32_e32 v163, s64, v142
	v_lshlrev_b32_e32 v142, 6, v163
	v_lshlrev_b32_e32 v143, 4, v162
	v_add3_u32 v166, s0, v142, v143
	v_and_b32_e32 v143, 64, v235
	v_xor_b32_e32 v142, 16, v235
	v_add_u32_e32 v143, 64, v143
	v_cmp_lt_i32_e32 vcc, v142, v143
	s_nop 1
	v_cndmask_b32_e32 v142, v235, v142, vcc
	v_lshlrev_b32_e32 v168, 2, v142
	v_xor_b32_e32 v142, 32, v235
	v_cmp_lt_i32_e32 vcc, v142, v143
	s_nop 1
	v_cndmask_b32_e32 v142, v235, v142, vcc
	v_lshlrev_b32_e32 v169, 2, v142
	ds_read_b128 v[142:145], v166
	s_andn2_b64 vcc, exec, s[36:37]
	s_waitcnt lgkmcnt(0)
	v_mov_b32_e32 v146, v143
	v_mov_b32_e32 v147, v144
	v_mov_b32_e32 v143, v145
	v_pk_add_f32 v[146:147], v[146:147], v[142:143]
	ds_read_b128 v[142:145], v166 offset:1024
	s_waitcnt lgkmcnt(0)
	v_mov_b32_e32 v148, v143
	v_mov_b32_e32 v149, v144
	v_mov_b32_e32 v143, v145
	v_pk_add_f32 v[142:143], v[148:149], v[142:143]
	v_mov_b32_e32 v145, v146
	v_mov_b32_e32 v144, v142
	v_mov_b32_e32 v146, v143
	v_pk_add_f32 v[142:143], v[144:145], v[146:147]
	ds_read_b128 v[146:149], v166 offset:2048
	ds_bpermute_b32 v145, v168, v143
	ds_bpermute_b32 v144, v168, v142
	s_waitcnt lgkmcnt(0)
	v_mov_b32_e32 v150, v147
	v_mov_b32_e32 v151, v148
	v_mov_b32_e32 v147, v149
	v_pk_add_f32 v[150:151], v[150:151], v[146:147]
	ds_read_b128 v[146:149], v166 offset:3072
	v_pk_add_f32 v[142:143], v[142:143], v[144:145]
	ds_bpermute_b32 v145, v169, v143
	ds_bpermute_b32 v144, v169, v142
	s_waitcnt lgkmcnt(0)
	v_mov_b32_e32 v152, v147
	v_mov_b32_e32 v153, v148
	v_mov_b32_e32 v147, v149
	v_pk_add_f32 v[146:147], v[152:153], v[146:147]
	v_mov_b32_e32 v149, v150
	v_mov_b32_e32 v148, v146
	v_mov_b32_e32 v150, v147
	v_pk_add_f32 v[146:147], v[148:149], v[150:151]
	ds_read_b128 v[150:153], v166 offset:8192
	ds_bpermute_b32 v149, v168, v147
	ds_bpermute_b32 v148, v168, v146
	s_waitcnt lgkmcnt(0)
	v_mov_b32_e32 v154, v151
	v_mov_b32_e32 v155, v152
	v_mov_b32_e32 v151, v153
	v_pk_add_f32 v[154:155], v[154:155], v[150:151]
	ds_read_b128 v[150:153], v166 offset:9216
	v_pk_add_f32 v[146:147], v[146:147], v[148:149]
	ds_bpermute_b32 v149, v169, v147
	ds_bpermute_b32 v148, v169, v146
	s_waitcnt lgkmcnt(0)
	v_mov_b32_e32 v156, v151
	v_mov_b32_e32 v157, v152
	v_mov_b32_e32 v151, v153
	v_pk_add_f32 v[150:151], v[156:157], v[150:151]
	v_mov_b32_e32 v153, v154
	v_mov_b32_e32 v152, v150
	v_mov_b32_e32 v154, v151
	v_pk_add_f32 v[150:151], v[152:153], v[154:155]
	ds_read_b128 v[154:157], v166 offset:10240
	ds_bpermute_b32 v153, v168, v151
	ds_bpermute_b32 v152, v168, v150
	s_waitcnt lgkmcnt(0)
	v_mov_b32_e32 v164, v155
	v_mov_b32_e32 v165, v156
	v_mov_b32_e32 v155, v157
	v_pk_add_f32 v[164:165], v[164:165], v[154:155]
	ds_read_b128 v[154:157], v166 offset:11264
	v_pk_add_f32 v[150:151], v[150:151], v[152:153]
	ds_bpermute_b32 v153, v169, v151
	ds_bpermute_b32 v152, v169, v150
	s_waitcnt lgkmcnt(0)
	s_waitcnt lgkmcnt(0)
	v_mov_b32_e32 v166, v155
	v_mov_b32_e32 v167, v156
	v_mov_b32_e32 v155, v157
	v_pk_add_f32 v[154:155], v[166:167], v[154:155]
	v_mov_b32_e32 v157, v164
	v_mov_b32_e32 v156, v154
	v_mov_b32_e32 v164, v155
	v_pk_add_f32 v[154:155], v[156:157], v[164:165]
	ds_bpermute_b32 v157, v168, v155
	ds_bpermute_b32 v156, v168, v154
	v_cndmask_b32_e64 v164, 0, 1, s[36:37]
	v_cmp_ne_u32_e64 s[38:39], 1, v164
	s_barrier
	s_waitcnt lgkmcnt(0)
	v_pk_add_f32 v[154:155], v[154:155], v[156:157]
	ds_bpermute_b32 v157, v169, v155
	ds_bpermute_b32 v156, v169, v154
	s_cbranch_vccnz .LBB0_228
	s_ashr_i32 s45, s44, 31
	s_lshl_b64 s[0:1], s[44:45], 14
	s_mov_b32 m0, s24
	v_lshl_add_u64 v[164:165], v[136:137], 0, s[0:1]
	s_mov_b64 s[0:1], 0x2000
	v_lshl_add_u64 v[166:167], v[164:165], 0, s[0:1]
	global_load_lds_dwordx4 v[164:165], off
	s_mov_b32 m0, s26
	s_nop 0
	global_load_lds_dwordx4 v[166:167], off
.LBB0_228:
	s_mov_b32 s0, 0x358637bd
	v_pk_add_f32 v[142:143], v[142:143], v[144:145]
	v_mov_b64_e32 v[164:165], s[0:1]
	v_pk_fma_f32 v[142:143], v[142:143], s[28:29], v[164:165] op_sel_hi:[1,0,0]
	v_pk_mul_f32 v[128:129], v[128:129], v[124:125]
	v_mul_f32_e32 v144, 0x4b800000, v143
	v_cmp_gt_f32_e64 s[0:1], s93, v143
	v_cmp_gt_f32_e32 vcc, s93, v142
	v_pk_mul_f32 v[120:121], v[120:121], v[116:117]
	v_cndmask_b32_e64 v143, v143, v144, s[0:1]
	v_rsq_f32_e32 v143, v143
	s_movk_i32 s8, 0x1600
	v_pk_mul_f32 v[112:113], v[112:113], v[108:109]
	v_pk_mul_f32 v[104:105], v[104:105], v[100:101]
	v_mul_f32_e32 v144, 0x45800000, v143
	v_cndmask_b32_e64 v166, v143, v144, s[0:1]
	v_mul_f32_e32 v143, 0x4b800000, v142
	v_cndmask_b32_e32 v142, v142, v143, vcc
	v_rsq_f32_e32 v142, v142
	v_pk_mul_f32 v[96:97], v[96:97], v[92:93]
	v_pk_mul_f32 v[88:89], v[88:89], v[84:85]
	v_pk_mul_f32 v[80:81], v[80:81], v[76:77]
	v_mul_f32_e32 v143, 0x45800000, v142
	v_cndmask_b32_e32 v167, v142, v143, vcc
	v_pk_add_f32 v[142:143], v[146:147], v[148:149]
	v_pk_mul_f32 v[72:73], v[72:73], v[68:69]
	v_pk_fma_f32 v[142:143], v[142:143], s[28:29], v[164:165] op_sel_hi:[1,0,0]
	v_pk_mul_f32 v[64:65], v[64:65], v[60:61]
	v_mul_f32_e32 v144, 0x4b800000, v143
	v_cmp_gt_f32_e64 s[0:1], s93, v143
	v_cmp_gt_f32_e32 vcc, s93, v142
	v_pk_mul_f32 v[56:57], v[56:57], v[52:53]
	v_cndmask_b32_e64 v143, v143, v144, s[0:1]
	v_rsq_f32_e32 v143, v143
	v_pk_mul_f32 v[48:49], v[48:49], v[44:45]
	v_pk_mul_f32 v[40:41], v[40:41], v[36:37]
	v_pk_mul_f32 v[32:33], v[32:33], v[28:29]
	v_mul_f32_e32 v144, 0x45800000, v143
	v_cndmask_b32_e64 v148, v143, v144, s[0:1]
	v_mul_f32_e32 v143, 0x4b800000, v142
	v_cndmask_b32_e32 v142, v142, v143, vcc
	v_rsq_f32_e32 v142, v142
	v_pk_mul_f32 v[24:25], v[24:25], v[20:21]
	v_pk_mul_f32 v[16:17], v[16:17], v[12:13]
	v_pk_mul_f32 v[8:9], v[8:9], v[4:5]
	v_mul_f32_e32 v143, 0x45800000, v142
	v_cndmask_b32_e32 v147, v142, v143, vcc
	v_pk_add_f32 v[142:143], v[150:151], v[152:153]
	v_mul_f32_e32 v152, 0xbfb8aa3b, v166
	v_pk_fma_f32 v[142:143], v[142:143], s[28:29], v[164:165] op_sel_hi:[1,0,0]
	v_pk_mul_f32 v[124:125], v[124:125], v[152:153] op_sel_hi:[1,0]
	v_mul_f32_e32 v144, 0x4b800000, v143
	v_cmp_gt_f32_e64 s[0:1], s93, v143
	v_cmp_gt_f32_e32 vcc, s93, v142
	v_exp_f32_e32 v124, v124
	v_cndmask_b32_e64 v143, v143, v144, s[0:1]
	v_rsq_f32_e32 v143, v143
	v_exp_f32_e32 v125, v125
	v_pk_mul_f32 v[116:117], v[116:117], v[152:153] op_sel_hi:[1,0]
	v_mul_f32_e32 v144, 0x45800000, v143
	v_cndmask_b32_e64 v146, v143, v144, s[0:1]
	v_mul_f32_e32 v143, 0x4b800000, v142
	v_cndmask_b32_e32 v142, v142, v143, vcc
	v_rsq_f32_e32 v142, v142
	v_pk_add_f32 v[124:125], v[124:125], 1.0 op_sel_hi:[1,0]
	v_exp_f32_e32 v116, v116
	v_rcp_f32_e32 v124, v124
	v_mul_f32_e32 v143, 0x45800000, v142
	v_cndmask_b32_e32 v145, v142, v143, vcc
	s_waitcnt lgkmcnt(0)
; __device__ __forceinline__ u32x4 pack8(f32x4 a, f32x4 b) { u32x4 w; w.x = cvt_pk_bf16(a[0], a[1]); w.y = cvt_pk_bf16(a[2], a[3]); w.z = cvt_pk_bf16(b[0], b[1]); w.w = cvt_pk_bf16(b[2], b[3]); return w; }
;     __device__ __forceinline__ void operator()(const Acc& acc, const Unit& u, int wr, int wc, int fr, int fq, const float (&rsv)[2][4]) const {
;         const int row0 = u.pm * 256 + wr * 64 + fr; const int hc = u.pn * 128 + wc * 32 + 8 * fq;
; #pragma unroll
;         for (int ai = 0; ai < 2; ++ai)
; #pragma unroll
;             for (int m = 0; m < 4; ++m) { const size_t row = (size_t)(row0 + ai * 128 + m * 16); const float rs = rsv[ai][m];
;                 const float c1 = rs * -1.4426950408889634f, c2 = rs * rs;
;                 f32x4 h[2];
; #pragma unroll
;                 for (int n = 0; n < 2; ++n)
; #pragma unroll
;                     for (int p = 0; p < 2; ++p) { const f32x2v g = (f32x2v){acc[ai][0][m][n][2 * p], acc[ai][0][m][n][2 * p + 1]}, uu = (f32x2v){acc[ai][1][m][n][2 * p], acc[ai][1][m][n][2 * p + 1]};
;                         const f32x2v a = g * c1; f32x2v d = (f32x2v){__builtin_amdgcn_exp2f(a.x), __builtin_amdgcn_exp2f(a.y)}; d = d + 1.0f;
;                         const f32x2v t = (f32x2v){__builtin_amdgcn_rcpf(d.x), __builtin_amdgcn_rcpf(d.y)}; const f32x2v hv = ((g * uu) * c2) * t;
;                         h[n][2 * p] = hv.x; h[n][2 * p + 1] = hv.y; }
;                 *(u32x4*)(H + row * DFF + hc) = pack8(h[0], h[1]); }
	v_pk_add_f32 v[142:143], v[154:155], v[156:157]
	v_rcp_f32_e32 v125, v125
	v_pk_fma_f32 v[142:143], v[142:143], s[28:29], v[164:165] op_sel_hi:[1,0,0]
	v_mul_f32_e32 v154, v166, v166
	v_mul_f32_e32 v144, 0x4b800000, v143
	v_cmp_gt_f32_e64 s[0:1], s93, v143
	v_pk_mul_f32 v[156:157], v[122:123], v[152:153] op_sel_hi:[1,0]
	v_pk_mul_f32 v[122:123], v[126:127], v[122:123]
	v_cndmask_b32_e64 v143, v143, v144, s[0:1]
	v_rsq_f32_e32 v143, v143
	v_pk_mul_f32 v[126:127], v[128:129], v[154:155] op_sel_hi:[1,0]
	v_exp_f32_e32 v156, v156
	v_pk_mul_f32 v[124:125], v[126:127], v[124:125]
	v_pk_mul_f32 v[126:127], v[114:115], v[152:153] op_sel_hi:[1,0]
	v_exp_f32_e32 v157, v157
	v_exp_f32_e32 v126, v126
	v_exp_f32_e32 v127, v127
	v_exp_f32_e32 v117, v117
	v_mul_f32_e32 v144, 0x45800000, v143
	v_cmp_gt_f32_e32 vcc, s93, v142
	v_cndmask_b32_e64 v144, v143, v144, s[0:1]
	v_mul_f32_e32 v143, 0x4b800000, v142
	v_cndmask_b32_e32 v142, v142, v143, vcc
	v_pk_add_f32 v[126:127], v[126:127], 1.0 op_sel_hi:[1,0]
	v_rsq_f32_e32 v142, v142
	v_pk_add_f32 v[156:157], v[156:157], 1.0 op_sel_hi:[1,0]
	v_rcp_f32_e32 v126, v126
	v_rcp_f32_e32 v127, v127
	v_pk_add_f32 v[116:117], v[116:117], 1.0 op_sel_hi:[1,0]
	v_rcp_f32_e32 v156, v156
	v_rcp_f32_e32 v157, v157
	v_rcp_f32_e32 v116, v116
	v_rcp_f32_e32 v117, v117
	s_lshl_b32 s0, s41, 7
	v_pk_mul_f32 v[114:115], v[118:119], v[114:115]
	s_or_b32 s0, s0, s73
	v_pk_mul_f32 v[114:115], v[114:115], v[154:155] op_sel_hi:[1,0]
	v_mul_f32_e32 v143, 0x45800000, v142
	v_lshl_add_u32 v150, v162, 3, s0
	v_pk_mul_f32 v[122:123], v[122:123], v[154:155] op_sel_hi:[1,0]
	v_pk_mul_f32 v[114:115], v[114:115], v[126:127]
	v_pk_mul_f32 v[118:119], v[120:121], v[154:155] op_sel_hi:[1,0]
	v_cndmask_b32_e32 v142, v142, v143, vcc
	v_lshl_add_u32 v143, s40, 8, v163
	v_ashrrev_i32_e32 v151, 31, v150
	v_pk_mul_f32 v[122:123], v[122:123], v[156:157]
	v_pk_mul_f32 v[116:117], v[118:119], v[116:117]
	v_cvt_pk_bf16_f32 v118, v122, v123
	v_cvt_pk_bf16_f32 v119, v124, v125
	v_cvt_pk_bf16_f32 v120, v114, v115
	v_mov_b64_e32 v[114:115], s[66:67]
	v_cvt_pk_bf16_f32 v121, v116, v117
	v_mad_i64_i32 v[122:123], s[0:1], v143, s8, v[114:115]
	v_lshlrev_b64 v[116:117], 1, v[150:151]
	v_lshl_add_u64 v[122:123], v[122:123], 0, v[116:117]
	global_store_dwordx4 v[122:123], v[118:121], off
	s_and_b64 vcc, exec, s[38:39]
	s_nop 0
	v_add_u32_e32 v119, 16, v143
	v_mul_f32_e32 v118, 0xbfb8aa3b, v167
	v_pk_mul_f32 v[108:109], v[108:109], v[118:119] op_sel_hi:[1,0]
	v_mul_f32_e32 v120, v167, v167
	v_exp_f32_e32 v108, v108
	v_exp_f32_e32 v109, v109
	v_pk_mul_f32 v[122:123], v[106:107], v[118:119] op_sel_hi:[1,0]
	v_pk_mul_f32 v[106:107], v[110:111], v[106:107]
	v_pk_mul_f32 v[110:111], v[112:113], v[120:121] op_sel_hi:[1,0]
	v_pk_add_f32 v[108:109], v[108:109], 1.0 op_sel_hi:[1,0]
	v_exp_f32_e32 v122, v122
	v_rcp_f32_e32 v108, v108
	v_rcp_f32_e32 v109, v109
	v_exp_f32_e32 v123, v123
	v_pk_mul_f32 v[106:107], v[106:107], v[120:121] op_sel_hi:[1,0]
	v_pk_mul_f32 v[108:109], v[110:111], v[108:109]
	v_pk_mul_f32 v[110:111], v[98:99], v[118:119] op_sel_hi:[1,0]
	v_pk_mul_f32 v[98:99], v[102:103], v[98:99]
	v_exp_f32_e32 v110, v110
	v_exp_f32_e32 v111, v111
	v_pk_mul_f32 v[98:99], v[98:99], v[120:121] op_sel_hi:[1,0]
	v_pk_add_f32 v[122:123], v[122:123], 1.0 op_sel_hi:[1,0]
	v_pk_add_f32 v[110:111], v[110:111], 1.0 op_sel_hi:[1,0]
	s_nop 0
	v_rcp_f32_e32 v110, v110
	v_rcp_f32_e32 v111, v111
	v_rcp_f32_e32 v122, v122
	v_rcp_f32_e32 v123, v123
	v_pk_mul_f32 v[102:103], v[98:99], v[110:111]
	v_pk_mul_f32 v[98:99], v[100:101], v[118:119] op_sel_hi:[1,0]
	v_pk_mul_f32 v[100:101], v[104:105], v[120:121] op_sel_hi:[1,0]
	v_exp_f32_e32 v98, v98
	v_exp_f32_e32 v99, v99
	v_pk_mul_f32 v[106:107], v[106:107], v[122:123]
	v_pk_add_f32 v[98:99], v[98:99], 1.0 op_sel_hi:[1,0]
	s_nop 0
	v_rcp_f32_e32 v98, v98
	v_rcp_f32_e32 v99, v99
	s_nop 0
	v_pk_mul_f32 v[104:105], v[100:101], v[98:99]
	v_cvt_pk_bf16_f32 v98, v106, v107
	v_cvt_pk_bf16_f32 v99, v108, v109
	v_cvt_pk_bf16_f32 v100, v102, v103
	v_mad_i64_i32 v[102:103], s[0:1], v119, s8, v[114:115]
	v_lshl_add_u64 v[102:103], v[102:103], 0, v[116:117]
	v_cvt_pk_bf16_f32 v101, v104, v105
	global_store_dwordx4 v[102:103], v[98:101], off
	s_nop 1
	v_add_u32_e32 v99, 32, v143
	v_mul_f32_e32 v98, 0xbfb8aa3b, v148
	v_pk_mul_f32 v[92:93], v[92:93], v[98:99] op_sel_hi:[1,0]
	v_mul_f32_e32 v100, v148, v148
	v_exp_f32_e32 v92, v92
	v_exp_f32_e32 v93, v93
	v_pk_mul_f32 v[102:103], v[90:91], v[98:99] op_sel_hi:[1,0]
	v_pk_mul_f32 v[90:91], v[94:95], v[90:91]
	v_pk_mul_f32 v[94:95], v[96:97], v[100:101] op_sel_hi:[1,0]
	v_pk_add_f32 v[92:93], v[92:93], 1.0 op_sel_hi:[1,0]
	v_exp_f32_e32 v102, v102
	v_rcp_f32_e32 v92, v92
	v_rcp_f32_e32 v93, v93
	v_exp_f32_e32 v103, v103
	v_pk_mul_f32 v[90:91], v[90:91], v[100:101] op_sel_hi:[1,0]
	v_pk_mul_f32 v[92:93], v[94:95], v[92:93]
	v_pk_mul_f32 v[94:95], v[82:83], v[98:99] op_sel_hi:[1,0]
	v_pk_mul_f32 v[82:83], v[86:87], v[82:83]
	v_exp_f32_e32 v94, v94
	v_exp_f32_e32 v95, v95
	v_pk_mul_f32 v[82:83], v[82:83], v[100:101] op_sel_hi:[1,0]
	v_pk_add_f32 v[102:103], v[102:103], 1.0 op_sel_hi:[1,0]
	v_pk_add_f32 v[94:95], v[94:95], 1.0 op_sel_hi:[1,0]
	s_nop 0
	v_rcp_f32_e32 v94, v94
	v_rcp_f32_e32 v95, v95
	v_rcp_f32_e32 v102, v102
	v_rcp_f32_e32 v103, v103
	v_pk_mul_f32 v[86:87], v[82:83], v[94:95]
	v_pk_mul_f32 v[82:83], v[84:85], v[98:99] op_sel_hi:[1,0]
	v_pk_mul_f32 v[84:85], v[88:89], v[100:101] op_sel_hi:[1,0]
	v_exp_f32_e32 v82, v82
	v_exp_f32_e32 v83, v83
	v_pk_mul_f32 v[90:91], v[90:91], v[102:103]
	v_pk_add_f32 v[82:83], v[82:83], 1.0 op_sel_hi:[1,0]
	s_nop 0
	v_rcp_f32_e32 v82, v82
	v_rcp_f32_e32 v83, v83
; __device__ __forceinline__ u32x4 pack8(f32x4 a, f32x4 b) { u32x4 w; w.x = cvt_pk_bf16(a[0], a[1]); w.y = cvt_pk_bf16(a[2], a[3]); w.z = cvt_pk_bf16(b[0], b[1]); w.w = cvt_pk_bf16(b[2], b[3]); return w; }
;     __device__ __forceinline__ void operator()(const Acc& acc, const Unit& u, int wr, int wc, int fr, int fq, const float (&rsv)[2][4]) const {
;         const int row0 = u.pm * 256 + wr * 64 + fr; const int hc = u.pn * 128 + wc * 32 + 8 * fq;
; #pragma unroll
;         for (int ai = 0; ai < 2; ++ai)
; #pragma unroll
;             for (int m = 0; m < 4; ++m) { const size_t row = (size_t)(row0 + ai * 128 + m * 16); const float rs = rsv[ai][m];
;                 const float c1 = rs * -1.4426950408889634f, c2 = rs * rs;
;                 f32x4 h[2];
; #pragma unroll
;                 for (int n = 0; n < 2; ++n)
; #pragma unroll
;                     for (int p = 0; p < 2; ++p) { const f32x2v g = (f32x2v){acc[ai][0][m][n][2 * p], acc[ai][0][m][n][2 * p + 1]}, uu = (f32x2v){acc[ai][1][m][n][2 * p], acc[ai][1][m][n][2 * p + 1]};
;                         const f32x2v a = g * c1; f32x2v d = (f32x2v){__builtin_amdgcn_exp2f(a.x), __builtin_amdgcn_exp2f(a.y)}; d = d + 1.0f;
;                         const f32x2v t = (f32x2v){__builtin_amdgcn_rcpf(d.x), __builtin_amdgcn_rcpf(d.y)}; const f32x2v hv = ((g * uu) * c2) * t;
;                         h[n][2 * p] = hv.x; h[n][2 * p + 1] = hv.y; }
;                 *(u32x4*)(H + row * DFF + hc) = pack8(h[0], h[1]); }
	s_nop 0
	v_pk_mul_f32 v[88:89], v[84:85], v[82:83]
	v_cvt_pk_bf16_f32 v82, v90, v91
	v_cvt_pk_bf16_f32 v83, v92, v93
	v_cvt_pk_bf16_f32 v84, v86, v87
	v_mad_i64_i32 v[86:87], s[0:1], v99, s8, v[114:115]
	v_lshl_add_u64 v[86:87], v[86:87], 0, v[116:117]
	v_cvt_pk_bf16_f32 v85, v88, v89
	global_store_dwordx4 v[86:87], v[82:85], off
	s_nop 1
	v_add_u32_e32 v83, 48, v143
	v_mul_f32_e32 v82, 0xbfb8aa3b, v147
	v_pk_mul_f32 v[76:77], v[76:77], v[82:83] op_sel_hi:[1,0]
	v_mul_f32_e32 v84, v147, v147
	v_exp_f32_e32 v76, v76
	v_exp_f32_e32 v77, v77
	v_pk_mul_f32 v[86:87], v[74:75], v[82:83] op_sel_hi:[1,0]
	v_pk_mul_f32 v[74:75], v[78:79], v[74:75]
	v_pk_mul_f32 v[78:79], v[80:81], v[84:85] op_sel_hi:[1,0]
	v_pk_add_f32 v[76:77], v[76:77], 1.0 op_sel_hi:[1,0]
	v_exp_f32_e32 v86, v86
	v_rcp_f32_e32 v76, v76
	v_rcp_f32_e32 v77, v77
	v_exp_f32_e32 v87, v87
	v_pk_mul_f32 v[74:75], v[74:75], v[84:85] op_sel_hi:[1,0]
	v_pk_mul_f32 v[76:77], v[78:79], v[76:77]
	v_pk_mul_f32 v[78:79], v[66:67], v[82:83] op_sel_hi:[1,0]
	v_pk_mul_f32 v[66:67], v[70:71], v[66:67]
	v_exp_f32_e32 v78, v78
	v_exp_f32_e32 v79, v79
	v_pk_mul_f32 v[66:67], v[66:67], v[84:85] op_sel_hi:[1,0]
	v_pk_add_f32 v[86:87], v[86:87], 1.0 op_sel_hi:[1,0]
	v_pk_add_f32 v[78:79], v[78:79], 1.0 op_sel_hi:[1,0]
	s_nop 0
	v_rcp_f32_e32 v78, v78
	v_rcp_f32_e32 v79, v79
	v_rcp_f32_e32 v86, v86
	v_rcp_f32_e32 v87, v87
	v_pk_mul_f32 v[70:71], v[66:67], v[78:79]
	v_pk_mul_f32 v[66:67], v[68:69], v[82:83] op_sel_hi:[1,0]
	v_pk_mul_f32 v[68:69], v[72:73], v[84:85] op_sel_hi:[1,0]
	v_exp_f32_e32 v66, v66
	v_exp_f32_e32 v67, v67
	v_pk_mul_f32 v[74:75], v[74:75], v[86:87]
	v_pk_add_f32 v[66:67], v[66:67], 1.0 op_sel_hi:[1,0]
	s_nop 0
	v_rcp_f32_e32 v66, v66
	v_rcp_f32_e32 v67, v67
	s_nop 0
	v_pk_mul_f32 v[72:73], v[68:69], v[66:67]
	v_cvt_pk_bf16_f32 v66, v74, v75
	v_cvt_pk_bf16_f32 v67, v76, v77
	v_cvt_pk_bf16_f32 v68, v70, v71
	v_mad_i64_i32 v[70:71], s[0:1], v83, s8, v[114:115]
	v_lshl_add_u64 v[70:71], v[70:71], 0, v[116:117]
	v_cvt_pk_bf16_f32 v69, v72, v73
	global_store_dwordx4 v[70:71], v[66:69], off
	s_nop 1
	v_add_u32_e32 v67, 0x80, v143
	v_mul_f32_e32 v66, 0xbfb8aa3b, v146
	v_pk_mul_f32 v[60:61], v[60:61], v[66:67] op_sel_hi:[1,0]
	v_mul_f32_e32 v68, v146, v146
	v_exp_f32_e32 v60, v60
	v_exp_f32_e32 v61, v61
	v_pk_mul_f32 v[70:71], v[58:59], v[66:67] op_sel_hi:[1,0]
	v_pk_mul_f32 v[58:59], v[62:63], v[58:59]
	v_pk_mul_f32 v[62:63], v[64:65], v[68:69] op_sel_hi:[1,0]
	v_pk_add_f32 v[60:61], v[60:61], 1.0 op_sel_hi:[1,0]
	v_exp_f32_e32 v70, v70
	v_rcp_f32_e32 v60, v60
	v_rcp_f32_e32 v61, v61
	v_exp_f32_e32 v71, v71
	v_pk_mul_f32 v[58:59], v[58:59], v[68:69] op_sel_hi:[1,0]
	v_pk_mul_f32 v[60:61], v[62:63], v[60:61]
	v_pk_mul_f32 v[62:63], v[50:51], v[66:67] op_sel_hi:[1,0]
	v_pk_mul_f32 v[50:51], v[54:55], v[50:51]
	v_exp_f32_e32 v62, v62
	v_exp_f32_e32 v63, v63
	v_pk_mul_f32 v[50:51], v[50:51], v[68:69] op_sel_hi:[1,0]
	v_pk_add_f32 v[70:71], v[70:71], 1.0 op_sel_hi:[1,0]
	v_pk_add_f32 v[62:63], v[62:63], 1.0 op_sel_hi:[1,0]
	s_nop 0
	v_rcp_f32_e32 v62, v62
	v_rcp_f32_e32 v63, v63
	v_rcp_f32_e32 v70, v70
	v_rcp_f32_e32 v71, v71
	v_pk_mul_f32 v[54:55], v[50:51], v[62:63]
	v_pk_mul_f32 v[50:51], v[52:53], v[66:67] op_sel_hi:[1,0]
	v_pk_mul_f32 v[52:53], v[56:57], v[68:69] op_sel_hi:[1,0]
	v_exp_f32_e32 v50, v50
	v_exp_f32_e32 v51, v51
	v_pk_mul_f32 v[58:59], v[58:59], v[70:71]
	v_pk_add_f32 v[50:51], v[50:51], 1.0 op_sel_hi:[1,0]
	s_nop 0
	v_rcp_f32_e32 v50, v50
	v_rcp_f32_e32 v51, v51
	s_nop 0
	v_pk_mul_f32 v[56:57], v[52:53], v[50:51]
	v_cvt_pk_bf16_f32 v50, v58, v59
	v_cvt_pk_bf16_f32 v51, v60, v61
	v_cvt_pk_bf16_f32 v52, v54, v55
	v_mad_i64_i32 v[54:55], s[0:1], v67, s8, v[114:115]
	v_lshl_add_u64 v[54:55], v[54:55], 0, v[116:117]
	v_cvt_pk_bf16_f32 v53, v56, v57
	global_store_dwordx4 v[54:55], v[50:53], off
	s_nop 1
	v_add_u32_e32 v51, 0x90, v143
	v_mul_f32_e32 v50, 0xbfb8aa3b, v145
	v_pk_mul_f32 v[44:45], v[44:45], v[50:51] op_sel_hi:[1,0]
	v_mul_f32_e32 v52, v145, v145
	v_exp_f32_e32 v44, v44
	v_exp_f32_e32 v45, v45
	v_pk_mul_f32 v[54:55], v[42:43], v[50:51] op_sel_hi:[1,0]
	v_pk_mul_f32 v[42:43], v[46:47], v[42:43]
	v_pk_mul_f32 v[46:47], v[48:49], v[52:53] op_sel_hi:[1,0]
	v_pk_add_f32 v[44:45], v[44:45], 1.0 op_sel_hi:[1,0]
	v_exp_f32_e32 v54, v54
	v_rcp_f32_e32 v44, v44
	v_rcp_f32_e32 v45, v45
	v_exp_f32_e32 v55, v55
	v_pk_mul_f32 v[42:43], v[42:43], v[52:53] op_sel_hi:[1,0]
	v_pk_mul_f32 v[44:45], v[46:47], v[44:45]
	v_pk_mul_f32 v[46:47], v[34:35], v[50:51] op_sel_hi:[1,0]
	v_pk_mul_f32 v[34:35], v[38:39], v[34:35]
	v_exp_f32_e32 v46, v46
	v_exp_f32_e32 v47, v47
; __device__ __forceinline__ u32x4 pack8(f32x4 a, f32x4 b) { u32x4 w; w.x = cvt_pk_bf16(a[0], a[1]); w.y = cvt_pk_bf16(a[2], a[3]); w.z = cvt_pk_bf16(b[0], b[1]); w.w = cvt_pk_bf16(b[2], b[3]); return w; }
; #define PG8_BAR __builtin_amdgcn_s_barrier()
; template <class Epi, class Sched>
; __device__ __forceinline__ void gemm_phase(LAS unsigned char* lds, const Gemm g, const Sched& S, const Epi& E) {
;     ...
;         if (!has_next) break;
; #pragma unroll
;         for (int a = 0; a < 2; ++a)
; #pragma unroll
;             for (int b = 0; b < 2; ++b)
; #pragma unroll
;                 for (int m = 0; m < 4; ++m)
; #pragma unroll
;                     for (int n = 0; n < 2; ++n) acc[a][b][m][n] = (f32x4){0.f, 0.f, 0.f, 0.f};
;         cur = nxt; cA = nA; cB = nB; ++ui;
;         if (wr == 1) PG8_BAR;
;     __device__ __forceinline__ void operator()(const Acc& acc, const Unit& u, int wr, int wc, int fr, int fq, const float (&rsv)[2][4]) const {
;     ...
;             for (int m = 0; m < 4; ++m) { const size_t row = (size_t)(row0 + ai * 128 + m * 16); const float rs = rsv[ai][m];
;                 const float c1 = rs * -1.4426950408889634f, c2 = rs * rs;
;                 f32x4 h[2];
; #pragma unroll
;                 for (int n = 0; n < 2; ++n)
; #pragma unroll
;                     for (int p = 0; p < 2; ++p) { const f32x2v g = (f32x2v){acc[ai][0][m][n][2 * p], acc[ai][0][m][n][2 * p + 1]}, uu = (f32x2v){acc[ai][1][m][n][2 * p], acc[ai][1][m][n][2 * p + 1]};
;                         const f32x2v a = g * c1; f32x2v d = (f32x2v){__builtin_amdgcn_exp2f(a.x), __builtin_amdgcn_exp2f(a.y)}; d = d + 1.0f;
;                         const f32x2v t = (f32x2v){__builtin_amdgcn_rcpf(d.x), __builtin_amdgcn_rcpf(d.y)}; const f32x2v hv = ((g * uu) * c2) * t;
;                         h[n][2 * p] = hv.x; h[n][2 * p + 1] = hv.y; }
;                 *(u32x4*)(H + row * DFF + hc) = pack8(h[0], h[1]); }
	v_pk_mul_f32 v[34:35], v[34:35], v[52:53] op_sel_hi:[1,0]
	v_pk_add_f32 v[54:55], v[54:55], 1.0 op_sel_hi:[1,0]
	v_pk_add_f32 v[46:47], v[46:47], 1.0 op_sel_hi:[1,0]
	s_nop 0
	v_rcp_f32_e32 v46, v46
	v_rcp_f32_e32 v47, v47
	v_rcp_f32_e32 v54, v54
	v_rcp_f32_e32 v55, v55
	v_pk_mul_f32 v[38:39], v[34:35], v[46:47]
	v_pk_mul_f32 v[34:35], v[36:37], v[50:51] op_sel_hi:[1,0]
	v_pk_mul_f32 v[36:37], v[40:41], v[52:53] op_sel_hi:[1,0]
	v_exp_f32_e32 v34, v34
	v_exp_f32_e32 v35, v35
	v_pk_mul_f32 v[42:43], v[42:43], v[54:55]
	v_pk_add_f32 v[34:35], v[34:35], 1.0 op_sel_hi:[1,0]
	s_nop 0
	v_rcp_f32_e32 v34, v34
	v_rcp_f32_e32 v35, v35
	s_nop 0
	v_pk_mul_f32 v[40:41], v[36:37], v[34:35]
	v_cvt_pk_bf16_f32 v34, v42, v43
	v_cvt_pk_bf16_f32 v35, v44, v45
	v_cvt_pk_bf16_f32 v36, v38, v39
	v_mad_i64_i32 v[38:39], s[0:1], v51, s8, v[114:115]
	v_lshl_add_u64 v[38:39], v[38:39], 0, v[116:117]
	v_cvt_pk_bf16_f32 v37, v40, v41
	global_store_dwordx4 v[38:39], v[34:37], off
	s_nop 1
	v_add_u32_e32 v35, 0xa0, v143
	v_mul_f32_e32 v34, 0xbfb8aa3b, v144
	v_pk_mul_f32 v[28:29], v[28:29], v[34:35] op_sel_hi:[1,0]
	v_mul_f32_e32 v36, v144, v144
	v_exp_f32_e32 v28, v28
	v_exp_f32_e32 v29, v29
	v_pk_mul_f32 v[38:39], v[26:27], v[34:35] op_sel_hi:[1,0]
	v_pk_mul_f32 v[26:27], v[30:31], v[26:27]
	v_pk_mul_f32 v[30:31], v[32:33], v[36:37] op_sel_hi:[1,0]
	v_pk_add_f32 v[28:29], v[28:29], 1.0 op_sel_hi:[1,0]
	v_exp_f32_e32 v38, v38
	v_rcp_f32_e32 v28, v28
	v_rcp_f32_e32 v29, v29
	v_exp_f32_e32 v39, v39
	v_pk_mul_f32 v[26:27], v[26:27], v[36:37] op_sel_hi:[1,0]
	v_pk_mul_f32 v[28:29], v[30:31], v[28:29]
	v_pk_mul_f32 v[30:31], v[18:19], v[34:35] op_sel_hi:[1,0]
	v_pk_mul_f32 v[18:19], v[22:23], v[18:19]
	v_exp_f32_e32 v30, v30
	v_exp_f32_e32 v31, v31
	v_pk_mul_f32 v[18:19], v[18:19], v[36:37] op_sel_hi:[1,0]
	v_pk_add_f32 v[38:39], v[38:39], 1.0 op_sel_hi:[1,0]
	v_pk_add_f32 v[30:31], v[30:31], 1.0 op_sel_hi:[1,0]
	s_nop 0
	v_rcp_f32_e32 v30, v30
	v_rcp_f32_e32 v31, v31
	v_rcp_f32_e32 v38, v38
	v_rcp_f32_e32 v39, v39
	v_pk_mul_f32 v[22:23], v[18:19], v[30:31]
	v_pk_mul_f32 v[18:19], v[20:21], v[34:35] op_sel_hi:[1,0]
	v_pk_mul_f32 v[20:21], v[24:25], v[36:37] op_sel_hi:[1,0]
	v_exp_f32_e32 v18, v18
	v_exp_f32_e32 v19, v19
	v_pk_mul_f32 v[26:27], v[26:27], v[38:39]
	v_pk_add_f32 v[18:19], v[18:19], 1.0 op_sel_hi:[1,0]
	s_nop 0
	v_rcp_f32_e32 v18, v18
	v_rcp_f32_e32 v19, v19
	s_nop 0
	v_pk_mul_f32 v[24:25], v[20:21], v[18:19]
	v_cvt_pk_bf16_f32 v18, v26, v27
	v_cvt_pk_bf16_f32 v19, v28, v29
	v_cvt_pk_bf16_f32 v20, v22, v23
	v_mad_i64_i32 v[22:23], s[0:1], v35, s8, v[114:115]
	v_lshl_add_u64 v[22:23], v[22:23], 0, v[116:117]
	v_cvt_pk_bf16_f32 v21, v24, v25
	global_store_dwordx4 v[22:23], v[18:21], off
	s_nop 1
	v_add_u32_e32 v19, 0xb0, v143
	v_mul_f32_e32 v18, 0xbfb8aa3b, v142
	v_pk_mul_f32 v[12:13], v[12:13], v[18:19] op_sel_hi:[1,0]
	v_mul_f32_e32 v20, v142, v142
	v_exp_f32_e32 v12, v12
	v_exp_f32_e32 v13, v13
	v_pk_mul_f32 v[22:23], v[10:11], v[18:19] op_sel_hi:[1,0]
	v_pk_mul_f32 v[10:11], v[14:15], v[10:11]
	v_pk_mul_f32 v[14:15], v[16:17], v[20:21] op_sel_hi:[1,0]
	v_pk_add_f32 v[12:13], v[12:13], 1.0 op_sel_hi:[1,0]
	v_exp_f32_e32 v22, v22
	v_rcp_f32_e32 v12, v12
	v_rcp_f32_e32 v13, v13
	v_exp_f32_e32 v23, v23
	v_pk_mul_f32 v[10:11], v[10:11], v[20:21] op_sel_hi:[1,0]
	v_pk_mul_f32 v[12:13], v[14:15], v[12:13]
	v_pk_mul_f32 v[14:15], v[2:3], v[18:19] op_sel_hi:[1,0]
	v_pk_mul_f32 v[2:3], v[6:7], v[2:3]
	v_exp_f32_e32 v14, v14
	v_exp_f32_e32 v15, v15
	v_pk_mul_f32 v[2:3], v[2:3], v[20:21] op_sel_hi:[1,0]
	v_pk_add_f32 v[22:23], v[22:23], 1.0 op_sel_hi:[1,0]
	v_pk_add_f32 v[14:15], v[14:15], 1.0 op_sel_hi:[1,0]
	s_nop 0
	v_rcp_f32_e32 v14, v14
	v_rcp_f32_e32 v15, v15
	v_rcp_f32_e32 v22, v22
	v_rcp_f32_e32 v23, v23
	v_pk_mul_f32 v[6:7], v[2:3], v[14:15]
	v_pk_mul_f32 v[2:3], v[4:5], v[18:19] op_sel_hi:[1,0]
	v_pk_mul_f32 v[4:5], v[8:9], v[20:21] op_sel_hi:[1,0]
	v_exp_f32_e32 v2, v2
	v_exp_f32_e32 v3, v3
	v_pk_mul_f32 v[10:11], v[10:11], v[22:23]
	v_pk_add_f32 v[2:3], v[2:3], 1.0 op_sel_hi:[1,0]
	s_nop 0
	v_rcp_f32_e32 v2, v2
	v_rcp_f32_e32 v3, v3
	s_nop 0
	v_pk_mul_f32 v[8:9], v[4:5], v[2:3]
	v_cvt_pk_bf16_f32 v2, v10, v11
	v_cvt_pk_bf16_f32 v3, v12, v13
	v_cvt_pk_bf16_f32 v4, v6, v7
	v_mad_i64_i32 v[6:7], s[0:1], v19, s8, v[114:115]
	v_lshl_add_u64 v[6:7], v[6:7], 0, v[116:117]
	s_mov_b64 s[0:1], -1
	v_cvt_pk_bf16_f32 v5, v8, v9
	global_store_dwordx4 v[6:7], v[2:5], off
	s_cbranch_vccnz .LBB0_217
	v_readlane_b32 s0, v250, 46
	v_readlane_b32 s1, v250, 47
	s_andn2_b64 vcc, exec, s[0:1]
	s_cbranch_vccnz .LBB0_216
	s_branch .LBB0_216
